# all 6 GEMM K-loops: LDS-DMA issues spread one per 2 MFMAs over first 2 sub-steps (was one per MFMA)
# speedup vs baseline: 1.0342x; 1.0033x over previous
.LBB0_34:
	s_add_i32 s1, s0, 0x10000
	s_and_b32 s13, s1, 0x10000
	s_and_b32 s0, s0, 0x10000
	s_add_i32 s0, s0, 16
	v_add_u32_e32 v190, s13, v210
	s_nop 0
	v_readfirstlane_b32 s13, v190
	s_waitcnt vmcnt(0)
	s_barrier
	v_add_u32_e32 v166, s0, v182
	v_add_u32_e32 v167, s0, v204
	v_add_u32_e32 v162, v166, v227
	v_add_u32_e32 v168, v167, v227
	ds_read_b128 v[150:153], v162
	ds_read_b128 v[154:157], v162 offset:4096
	ds_read_b128 v[158:161], v162 offset:8192
	ds_read_b128 v[162:165], v162 offset:12288
	ds_read_b128 v[170:173], v168 offset:32768
	ds_read_b128 v[174:177], v168 offset:36864
	v_lshl_add_u64 v[178:179], v[142:143], 0, s[2:3]
	s_mov_b32 m0, s13
	s_nop 0
	global_load_lds_dwordx4 v[178:179], off
	s_waitcnt lgkmcnt(1)
	v_mfma_f32_32x32x16_bf16 v[112:127], v[170:173], v[150:153], v[112:127]
	v_lshl_add_u64 v[178:179], v[140:141], 0, s[2:3]
	s_add_i32 s14, s13, 0x2000
	s_mov_b32 m0, s14
	s_nop 0
	global_load_lds_dwordx4 v[178:179], off
	v_add_u32_e32 v168, v167, v228
	v_mfma_f32_32x32x16_bf16 v[96:111], v[170:173], v[154:157], v[96:111]
	v_mfma_f32_32x32x16_bf16 v[80:95], v[170:173], v[158:161], v[80:95]
	v_lshl_add_u64 v[178:179], v[138:139], 0, s[2:3]
	s_add_i32 s14, s13, 0x4000
	s_mov_b32 m0, s14
	s_nop 0
	global_load_lds_dwordx4 v[178:179], off
	v_mfma_f32_32x32x16_bf16 v[64:79], v[170:173], v[162:165], v[64:79]
	s_waitcnt lgkmcnt(0)
	v_mfma_f32_32x32x16_bf16 v[48:63], v[174:177], v[150:153], v[48:63]
	v_lshl_add_u64 v[178:179], v[136:137], 0, s[2:3]
	s_add_i32 s14, s13, 0x6000
	s_mov_b32 m0, s14
	s_nop 0
	global_load_lds_dwordx4 v[178:179], off
	v_mfma_f32_32x32x16_bf16 v[32:47], v[174:177], v[154:157], v[32:47]
	v_mfma_f32_32x32x16_bf16 v[16:31], v[174:177], v[158:161], v[16:31]
	v_lshl_add_u64 v[178:179], v[134:135], 0, s[2:3]
	s_add_i32 s14, s13, 0x8000
	s_mov_b32 m0, s14
	s_nop 0
	global_load_lds_dwordx4 v[178:179], off
	v_mfma_f32_32x32x16_bf16 v[0:15], v[174:177], v[162:165], v[0:15]
	v_add_u32_e32 v162, v166, v228
	ds_read_b128 v[150:153], v162
	ds_read_b128 v[154:157], v162 offset:4096
	ds_read_b128 v[158:161], v162 offset:8192
	ds_read_b128 v[162:165], v162 offset:12288
	ds_read_b128 v[170:173], v168 offset:32768
	ds_read_b128 v[174:177], v168 offset:36864
	v_add_u32_e32 v168, v167, v229
	s_waitcnt lgkmcnt(1)
	v_mfma_f32_32x32x16_bf16 v[112:127], v[170:173], v[150:153], v[112:127]
	v_lshl_add_u64 v[178:179], v[132:133], 0, s[2:3]
	s_add_i32 s14, s13, 0xa000
	s_mov_b32 m0, s14
	s_nop 0
	global_load_lds_dwordx4 v[178:179], off
	v_mfma_f32_32x32x16_bf16 v[96:111], v[170:173], v[154:157], v[96:111]
	v_mfma_f32_32x32x16_bf16 v[80:95], v[170:173], v[158:161], v[80:95]
	v_lshl_add_u64 v[178:179], v[130:131], 0, s[2:3]
	s_add_i32 s14, s13, 0xc000
	s_mov_b32 m0, s14
	s_nop 0
	global_load_lds_dwordx4 v[178:179], off
	v_mfma_f32_32x32x16_bf16 v[64:79], v[170:173], v[162:165], v[64:79]
	s_waitcnt lgkmcnt(0)
	v_mfma_f32_32x32x16_bf16 v[48:63], v[174:177], v[150:153], v[48:63]
	v_lshl_add_u64 v[178:179], v[128:129], 0, s[2:3]
	s_add_i32 s14, s13, 0xe000
	s_mov_b32 m0, s14
	s_nop 0
	global_load_lds_dwordx4 v[178:179], off
	s_add_u32 s2, s2, 0x80
	s_addc_u32 s3, s3, 0
	s_cmpk_lg_i32 s2, 0x1f80
	v_mfma_f32_32x32x16_bf16 v[32:47], v[174:177], v[154:157], v[32:47]
	v_mfma_f32_32x32x16_bf16 v[16:31], v[174:177], v[158:161], v[16:31]
	v_mfma_f32_32x32x16_bf16 v[0:15], v[174:177], v[162:165], v[0:15]
	v_add_u32_e32 v162, v166, v229
	ds_read_b128 v[150:153], v162
	ds_read_b128 v[154:157], v162 offset:4096
	ds_read_b128 v[158:161], v162 offset:8192
	ds_read_b128 v[162:165], v162 offset:12288
	ds_read_b128 v[170:173], v168 offset:32768
	ds_read_b128 v[174:177], v168 offset:36864
	s_waitcnt lgkmcnt(1)
	v_mfma_f32_32x32x16_bf16 v[112:127], v[170:173], v[150:153], v[112:127]
	v_mfma_f32_32x32x16_bf16 v[96:111], v[170:173], v[154:157], v[96:111]
	v_mfma_f32_32x32x16_bf16 v[80:95], v[170:173], v[158:161], v[80:95]
	v_mfma_f32_32x32x16_bf16 v[64:79], v[170:173], v[162:165], v[64:79]
	s_waitcnt lgkmcnt(0)
	v_mfma_f32_32x32x16_bf16 v[48:63], v[174:177], v[150:153], v[48:63]
	v_mfma_f32_32x32x16_bf16 v[32:47], v[174:177], v[154:157], v[32:47]
	v_mfma_f32_32x32x16_bf16 v[16:31], v[174:177], v[158:161], v[16:31]
	v_mfma_f32_32x32x16_bf16 v[0:15], v[174:177], v[162:165], v[0:15]
	v_add_u32_e32 v162, v166, v230
	v_add_u32_e32 v166, v167, v230
	ds_read_b128 v[150:153], v162
	ds_read_b128 v[154:157], v162 offset:4096
	ds_read_b128 v[158:161], v162 offset:8192
	ds_read_b128 v[162:165], v162 offset:12288
	ds_read_b128 v[170:173], v166 offset:32768
	ds_read_b128 v[174:177], v166 offset:36864
	s_waitcnt lgkmcnt(1)
	v_mfma_f32_32x32x16_bf16 v[112:127], v[170:173], v[150:153], v[112:127]
	v_mfma_f32_32x32x16_bf16 v[96:111], v[170:173], v[154:157], v[96:111]
	v_mfma_f32_32x32x16_bf16 v[80:95], v[170:173], v[158:161], v[80:95]
	v_mfma_f32_32x32x16_bf16 v[64:79], v[170:173], v[162:165], v[64:79]
	s_waitcnt lgkmcnt(0)
	v_mfma_f32_32x32x16_bf16 v[48:63], v[174:177], v[150:153], v[48:63]
	v_mfma_f32_32x32x16_bf16 v[32:47], v[174:177], v[154:157], v[32:47]
	v_mfma_f32_32x32x16_bf16 v[16:31], v[174:177], v[158:161], v[16:31]
	v_mfma_f32_32x32x16_bf16 v[0:15], v[174:177], v[162:165], v[0:15]
	s_mov_b32 s0, s1
	s_cbranch_scc1 .LBB0_34
	s_add_i32 s23, s23, s78
	s_cmpk_gt_i32 s23, 0xff
	s_waitcnt vmcnt(0)
	s_barrier
	s_cselect_b64 s[2:3], -1, 0
	s_and_b64 vcc, exec, s[2:3]
	s_cbranch_vccnz .LBB0_37
	s_lshl_b32 s0, s23, 3
	s_lshr_b32 s1, s23, 5
	s_and_b32 s0, s0, 56
	s_add_i32 s0, s0, s1
	s_lshl_b32 s10, s23, 5
	v_lshl_add_u32 v130, s0, 8, v207
	s_and_b32 s10, s10, 0x300
	v_ashrrev_i32_e32 v131, 31, v130
	v_lshlrev_b64 v[132:133], 13, v[130:131]
	s_cmp_lg_u32 16, -1
	v_lshl_add_u64 v[132:133], v[146:147], 0, v[132:133]
	v_readfirstlane_b32 s0, v209
	s_cselect_b32 s1, 16, 0
	s_add_i32 s0, s0, s1
	s_mov_b32 s1, m0
	s_mov_b32 m0, s0
	s_nop 0
	global_load_lds_dwordx4 v[132:133], off
	s_mov_b32 m0, s1
	v_add_u32_e32 v132, 64, v130
	v_ashrrev_i32_e32 v133, 31, v132
	v_lshlrev_b64 v[132:133], 13, v[132:133]
	v_lshl_add_u64 v[132:133], v[146:147], 0, v[132:133]
	v_add_u32_e32 v128, s10, v208
	s_add_i32 s1, s0, 0x2000
	s_mov_b32 s10, m0
	s_mov_b32 m0, s1
	s_nop 0
	global_load_lds_dwordx4 v[132:133], off
	s_mov_b32 m0, s10
	v_add_u32_e32 v132, 0x80, v130
	v_ashrrev_i32_e32 v133, 31, v132
	v_add_u32_e32 v130, 0xc0, v130
	v_lshlrev_b64 v[132:133], 13, v[132:133]
	v_ashrrev_i32_e32 v131, 31, v130
	v_lshl_add_u64 v[132:133], v[146:147], 0, v[132:133]
	s_add_i32 s1, s0, 0x4000
	s_mov_b32 s10, m0
	s_mov_b32 m0, s1
	s_nop 0
	global_load_lds_dwordx4 v[132:133], off
	s_mov_b32 m0, s10
	v_lshlrev_b64 v[130:131], 13, v[130:131]
	v_ashrrev_i32_e32 v129, 31, v128
	v_lshl_add_u64 v[130:131], v[146:147], 0, v[130:131]
	s_add_i32 s1, s0, 0x6000
	s_mov_b32 s10, m0
	s_mov_b32 m0, s1
	s_nop 0
	global_load_lds_dwordx4 v[130:131], off
	s_mov_b32 m0, s10
	v_lshlrev_b64 v[128:129], 13, v[128:129]
	v_lshl_add_u64 v[128:129], v[144:145], 0, v[128:129]
	s_mov_b64 s[10:11], 0x200000
	v_lshl_add_u64 v[130:131], v[128:129], 0, s[10:11]
	s_add_i32 s1, s0, 0x8000
	s_mov_b32 s10, m0
	s_mov_b32 m0, s1
	s_nop 0
	global_load_lds_dwordx4 v[130:131], off
	s_mov_b32 m0, s10
	s_mov_b64 s[10:11], 0x280000
	v_lshl_add_u64 v[130:131], v[128:129], 0, s[10:11]
	s_add_i32 s1, s0, 0xa000
	s_mov_b32 s10, m0
	s_mov_b32 m0, s1
	s_nop 0
	global_load_lds_dwordx4 v[130:131], off
	s_mov_b32 m0, s10
	s_mov_b64 s[10:11], 0x300000
	v_lshl_add_u64 v[130:131], v[128:129], 0, s[10:11]
	s_add_i32 s1, s0, 0xc000
	s_mov_b32 s10, m0
	s_mov_b32 m0, s1
	s_nop 0
	global_load_lds_dwordx4 v[130:131], off
	s_mov_b32 m0, s10
	s_mov_b64 s[10:11], 0x380000
	v_lshl_add_u64 v[128:129], v[128:129], 0, s[10:11]
	s_add_i32 s0, s0, 0xe000
	s_mov_b32 s1, m0
	s_mov_b32 m0, s0
	s_nop 0
	global_load_lds_dwordx4 v[128:129], off
	s_mov_b32 m0, s1
	s_mov_b64 s[10:11], -1

.LBB0_702:
	s_add_i32 s1, s0, 0x10000
	s_and_b32 s14, s1, 0x10000
	s_and_b32 s0, s0, 0x10000
	s_add_i32 s0, s0, 16
	v_add_u32_e32 v190, s14, v161
	s_nop 0
	v_readfirstlane_b32 s14, v190
	s_waitcnt vmcnt(0)
	s_barrier
	v_add_u32_e32 v133, s0, v151
	v_add_u32_e32 v168, v133, v166
	ds_read_b128 v[178:181], v168
	ds_read_b128 v[202:205], v168 offset:4096
	ds_read_b128 v[206:209], v168 offset:8192
	ds_read_b128 v[210:213], v168 offset:12288
	v_add_u32_e32 v168, s0, v155
	v_add_u32_e32 v177, v168, v166
	ds_read_b128 v[214:217], v177 offset:32768
	ds_read_b128 v[218:221], v177 offset:36864
	v_lshl_add_u64 v[222:223], v[148:149], 0, s[2:3]
	s_mov_b32 m0, s14
	s_nop 0
	global_load_lds_dwordx4 v[222:223], off
	s_waitcnt lgkmcnt(1)
	v_mfma_f32_32x32x16_bf16 v[112:127], v[214:217], v[178:181], v[112:127]
	v_lshl_add_u64 v[222:223], v[146:147], 0, s[2:3]
	s_add_i32 s15, s14, 0x2000
	s_mov_b32 m0, s15
	s_nop 0
	global_load_lds_dwordx4 v[222:223], off
	v_add_u32_e32 v177, v133, v167
	v_mfma_f32_32x32x16_bf16 v[80:95], v[214:217], v[202:205], v[80:95]
	v_mfma_f32_32x32x16_bf16 v[48:63], v[214:217], v[206:209], v[48:63]
	v_lshl_add_u64 v[222:223], v[144:145], 0, s[2:3]
	s_add_i32 s15, s14, 0x4000
	s_mov_b32 m0, s15
	s_nop 0
	global_load_lds_dwordx4 v[222:223], off
	v_mfma_f32_32x32x16_bf16 v[16:31], v[214:217], v[210:213], v[16:31]
	s_waitcnt lgkmcnt(0)
	v_mfma_f32_32x32x16_bf16 v[96:111], v[218:221], v[178:181], v[96:111]
	v_lshl_add_u64 v[222:223], v[142:143], 0, s[2:3]
	s_add_i32 s15, s14, 0x6000
	s_mov_b32 m0, s15
	s_nop 0
	global_load_lds_dwordx4 v[222:223], off
	v_mfma_f32_32x32x16_bf16 v[64:79], v[218:221], v[202:205], v[64:79]
	v_mfma_f32_32x32x16_bf16 v[32:47], v[218:221], v[206:209], v[32:47]
	v_lshl_add_u64 v[222:223], v[140:141], 0, s[2:3]
	s_add_i32 s15, s14, 0x8000
	s_mov_b32 m0, s15
	s_nop 0
	global_load_lds_dwordx4 v[222:223], off
	v_mfma_f32_32x32x16_bf16 v[0:15], v[218:221], v[210:213], v[0:15]
	ds_read_b128 v[178:181], v177
	ds_read_b128 v[202:205], v177 offset:4096
	ds_read_b128 v[206:209], v177 offset:8192
	ds_read_b128 v[210:213], v177 offset:12288
	v_add_u32_e32 v177, v168, v167
	ds_read_b128 v[214:217], v177 offset:32768
	ds_read_b128 v[218:221], v177 offset:36864
	v_add_u32_e32 v177, v133, v170
	v_add_u32_e32 v133, v133, v171
	s_waitcnt lgkmcnt(1)
	v_mfma_f32_32x32x16_bf16 v[112:127], v[214:217], v[178:181], v[112:127]
	v_lshl_add_u64 v[222:223], v[138:139], 0, s[2:3]
	s_add_i32 s15, s14, 0xa000
	s_mov_b32 m0, s15
	s_nop 0
	global_load_lds_dwordx4 v[222:223], off
	v_mfma_f32_32x32x16_bf16 v[80:95], v[214:217], v[202:205], v[80:95]
	v_mfma_f32_32x32x16_bf16 v[48:63], v[214:217], v[206:209], v[48:63]
	v_lshl_add_u64 v[222:223], v[136:137], 0, s[2:3]
	s_add_i32 s15, s14, 0xc000
	s_mov_b32 m0, s15
	s_nop 0
	global_load_lds_dwordx4 v[222:223], off
	v_mfma_f32_32x32x16_bf16 v[16:31], v[214:217], v[210:213], v[16:31]
	s_waitcnt lgkmcnt(0)
	v_mfma_f32_32x32x16_bf16 v[96:111], v[218:221], v[178:181], v[96:111]
	v_lshl_add_u64 v[222:223], v[134:135], 0, s[2:3]
	s_add_i32 s15, s14, 0xe000
	s_mov_b32 m0, s15
	s_nop 0
	global_load_lds_dwordx4 v[222:223], off
	s_add_u32 s2, s2, 0x80
	s_addc_u32 s3, s3, 0
	s_cmpk_eq_i32 s2, 0x780
	v_mfma_f32_32x32x16_bf16 v[64:79], v[218:221], v[202:205], v[64:79]
	v_mfma_f32_32x32x16_bf16 v[32:47], v[218:221], v[206:209], v[32:47]
	v_mfma_f32_32x32x16_bf16 v[0:15], v[218:221], v[210:213], v[0:15]
	ds_read_b128 v[178:181], v177
	ds_read_b128 v[202:205], v177 offset:4096
	ds_read_b128 v[206:209], v177 offset:8192
	ds_read_b128 v[210:213], v177 offset:12288
	v_add_u32_e32 v177, v168, v170
	ds_read_b128 v[214:217], v177 offset:32768
	ds_read_b128 v[218:221], v177 offset:36864
	s_waitcnt lgkmcnt(1)
	v_mfma_f32_32x32x16_bf16 v[112:127], v[214:217], v[178:181], v[112:127]
	v_mfma_f32_32x32x16_bf16 v[80:95], v[214:217], v[202:205], v[80:95]
	v_mfma_f32_32x32x16_bf16 v[48:63], v[214:217], v[206:209], v[48:63]
	v_mfma_f32_32x32x16_bf16 v[16:31], v[214:217], v[210:213], v[16:31]
	s_waitcnt lgkmcnt(0)
	v_mfma_f32_32x32x16_bf16 v[96:111], v[218:221], v[178:181], v[96:111]
	v_mfma_f32_32x32x16_bf16 v[64:79], v[218:221], v[202:205], v[64:79]
	v_mfma_f32_32x32x16_bf16 v[32:47], v[218:221], v[206:209], v[32:47]
	v_mfma_f32_32x32x16_bf16 v[0:15], v[218:221], v[210:213], v[0:15]
	ds_read_b128 v[178:181], v133
	ds_read_b128 v[202:205], v133 offset:4096
	ds_read_b128 v[206:209], v133 offset:8192
	ds_read_b128 v[210:213], v133 offset:12288
	v_add_u32_e32 v133, v168, v171
	ds_read_b128 v[214:217], v133 offset:32768
	ds_read_b128 v[218:221], v133 offset:36864
	s_waitcnt lgkmcnt(1)
	v_mfma_f32_32x32x16_bf16 v[112:127], v[214:217], v[178:181], v[112:127]
	v_mfma_f32_32x32x16_bf16 v[80:95], v[214:217], v[202:205], v[80:95]
	v_mfma_f32_32x32x16_bf16 v[48:63], v[214:217], v[206:209], v[48:63]
	v_mfma_f32_32x32x16_bf16 v[16:31], v[214:217], v[210:213], v[16:31]
	s_waitcnt lgkmcnt(0)
	v_mfma_f32_32x32x16_bf16 v[96:111], v[218:221], v[178:181], v[96:111]
	v_mfma_f32_32x32x16_bf16 v[64:79], v[218:221], v[202:205], v[64:79]
	v_mfma_f32_32x32x16_bf16 v[32:47], v[218:221], v[206:209], v[32:47]
	v_mfma_f32_32x32x16_bf16 v[0:15], v[218:221], v[210:213], v[0:15]
	s_mov_b32 s0, s1
	s_cbranch_scc0 .LBB0_702
	s_waitcnt vmcnt(0)
	s_barrier
	v_mov_b32_e32 v133, 0x358637bd
	s_and_saveexec_b64 s[2:3], s[6:7]
	s_cbranch_execz .LBB0_705
	v_add_u32_e32 v134, s17, v150
	v_ashrrev_i32_e32 v135, 31, v134
	v_lshlrev_b64 v[134:135], 6, v[134:135]
	v_lshl_add_u64 v[146:147], s[10:11], 0, v[134:135]
	global_load_dwordx4 v[134:137], v[146:147], off
	global_load_dwordx4 v[138:141], v[146:147], off offset:16
	global_load_dwordx4 v[142:145], v[146:147], off offset:32
	s_nop 0
	global_load_dwordx4 v[146:149], v[146:147], off offset:48
	s_waitcnt vmcnt(3)
	v_mov_b32_e32 v178, v135
	v_mov_b32_e32 v179, v136
	v_mov_b32_e32 v135, v137
	v_pk_add_f32 v[134:135], v[178:179], v[134:135]
	s_waitcnt vmcnt(2)
	v_mov_b32_e32 v180, v139
	v_mov_b32_e32 v181, v140
	v_mov_b32_e32 v139, v141
	v_add_f32_e32 v133, 0, v134
	v_pk_add_f32 v[136:137], v[180:181], v[138:139]
	v_add_f32_e32 v133, v133, v135
	s_waitcnt vmcnt(1)
	v_mov_b32_e32 v182, v143
	v_mov_b32_e32 v183, v144
	v_mov_b32_e32 v143, v145
	v_add_f32_e32 v133, v133, v136
	v_pk_add_f32 v[138:139], v[182:183], v[142:143]
	v_add_f32_e32 v133, v133, v137
	s_waitcnt vmcnt(0)
	v_mov_b32_e32 v202, v147
	v_mov_b32_e32 v203, v148
	v_mov_b32_e32 v147, v149
	v_add_f32_e32 v133, v133, v138
	v_add_f32_e32 v133, v133, v139
	v_pk_add_f32 v[134:135], v[202:203], v[146:147]
	s_nop 0
	v_add_f32_e32 v133, v133, v134
	v_add_f32_e32 v133, v133, v135
	v_fmamk_f32 v133, v133, 0x3a800000, v187

.LBB0_717:
	s_add_i32 s1, s0, 0x10000
	s_and_b32 s11, s1, 0x10000
	s_and_b32 s0, s0, 0x10000
	s_add_i32 s0, s0, 16
	v_add_u32_e32 v190, s11, v210
	s_nop 0
	v_readfirstlane_b32 s11, v190
	s_waitcnt vmcnt(0)
	s_barrier
	v_add_u32_e32 v166, s0, v182
	v_add_u32_e32 v167, s0, v204
	v_add_u32_e32 v162, v166, v227
	v_add_u32_e32 v168, v167, v227
	ds_read_b128 v[150:153], v162
	ds_read_b128 v[154:157], v162 offset:4096
	ds_read_b128 v[158:161], v162 offset:8192
	ds_read_b128 v[162:165], v162 offset:12288
	ds_read_b128 v[170:173], v168 offset:32768
	ds_read_b128 v[174:177], v168 offset:36864
	v_lshl_add_u64 v[178:179], v[142:143], 0, s[2:3]
	s_mov_b32 m0, s11
	s_nop 0
	global_load_lds_dwordx4 v[178:179], off
	s_waitcnt lgkmcnt(1)
	v_mfma_f32_32x32x16_bf16 v[112:127], v[170:173], v[150:153], v[112:127]
	v_lshl_add_u64 v[178:179], v[140:141], 0, s[2:3]
	s_add_i32 s12, s11, 0x2000
	s_mov_b32 m0, s12
	s_nop 0
	global_load_lds_dwordx4 v[178:179], off
	v_add_u32_e32 v168, v167, v228
	v_mfma_f32_32x32x16_bf16 v[96:111], v[170:173], v[154:157], v[96:111]
	v_mfma_f32_32x32x16_bf16 v[80:95], v[170:173], v[158:161], v[80:95]
	v_lshl_add_u64 v[178:179], v[138:139], 0, s[2:3]
	s_add_i32 s12, s11, 0x4000
	s_mov_b32 m0, s12
	s_nop 0
	global_load_lds_dwordx4 v[178:179], off
	v_mfma_f32_32x32x16_bf16 v[64:79], v[170:173], v[162:165], v[64:79]
	s_waitcnt lgkmcnt(0)
	v_mfma_f32_32x32x16_bf16 v[48:63], v[174:177], v[150:153], v[48:63]
	v_lshl_add_u64 v[178:179], v[136:137], 0, s[2:3]
	s_add_i32 s12, s11, 0x6000
	s_mov_b32 m0, s12
	s_nop 0
	global_load_lds_dwordx4 v[178:179], off
	v_mfma_f32_32x32x16_bf16 v[32:47], v[174:177], v[154:157], v[32:47]
	v_mfma_f32_32x32x16_bf16 v[16:31], v[174:177], v[158:161], v[16:31]
	v_lshl_add_u64 v[178:179], v[134:135], 0, s[2:3]
	s_add_i32 s12, s11, 0x8000
	s_mov_b32 m0, s12
	s_nop 0
	global_load_lds_dwordx4 v[178:179], off
	v_mfma_f32_32x32x16_bf16 v[0:15], v[174:177], v[162:165], v[0:15]
	v_add_u32_e32 v162, v166, v228
	ds_read_b128 v[150:153], v162
	ds_read_b128 v[154:157], v162 offset:4096
	ds_read_b128 v[158:161], v162 offset:8192
	ds_read_b128 v[162:165], v162 offset:12288
	ds_read_b128 v[170:173], v168 offset:32768
	ds_read_b128 v[174:177], v168 offset:36864
	v_add_u32_e32 v168, v167, v229
	s_waitcnt lgkmcnt(1)
	v_mfma_f32_32x32x16_bf16 v[112:127], v[170:173], v[150:153], v[112:127]
	v_lshl_add_u64 v[178:179], v[132:133], 0, s[2:3]
	s_add_i32 s12, s11, 0xa000
	s_mov_b32 m0, s12
	s_nop 0
	global_load_lds_dwordx4 v[178:179], off
	v_mfma_f32_32x32x16_bf16 v[96:111], v[170:173], v[154:157], v[96:111]
	v_mfma_f32_32x32x16_bf16 v[80:95], v[170:173], v[158:161], v[80:95]
	v_lshl_add_u64 v[178:179], v[130:131], 0, s[2:3]
	s_add_i32 s12, s11, 0xc000
	s_mov_b32 m0, s12
	s_nop 0
	global_load_lds_dwordx4 v[178:179], off
	v_mfma_f32_32x32x16_bf16 v[64:79], v[170:173], v[162:165], v[64:79]
	s_waitcnt lgkmcnt(0)
	v_mfma_f32_32x32x16_bf16 v[48:63], v[174:177], v[150:153], v[48:63]
	v_lshl_add_u64 v[178:179], v[128:129], 0, s[2:3]
	s_add_i32 s12, s11, 0xe000
	s_mov_b32 m0, s12
	s_nop 0
	global_load_lds_dwordx4 v[178:179], off
	s_add_u32 s2, s2, 0x80
	s_addc_u32 s3, s3, 0
	s_cmpk_lg_i32 s2, 0x780
	v_mfma_f32_32x32x16_bf16 v[32:47], v[174:177], v[154:157], v[32:47]
	v_mfma_f32_32x32x16_bf16 v[16:31], v[174:177], v[158:161], v[16:31]
	v_mfma_f32_32x32x16_bf16 v[0:15], v[174:177], v[162:165], v[0:15]
	v_add_u32_e32 v162, v166, v229
	ds_read_b128 v[150:153], v162
	ds_read_b128 v[154:157], v162 offset:4096
	ds_read_b128 v[158:161], v162 offset:8192
	ds_read_b128 v[162:165], v162 offset:12288
	ds_read_b128 v[170:173], v168 offset:32768
	ds_read_b128 v[174:177], v168 offset:36864
	s_waitcnt lgkmcnt(1)
	v_mfma_f32_32x32x16_bf16 v[112:127], v[170:173], v[150:153], v[112:127]
	v_mfma_f32_32x32x16_bf16 v[96:111], v[170:173], v[154:157], v[96:111]
	v_mfma_f32_32x32x16_bf16 v[80:95], v[170:173], v[158:161], v[80:95]
	v_mfma_f32_32x32x16_bf16 v[64:79], v[170:173], v[162:165], v[64:79]
	s_waitcnt lgkmcnt(0)
	v_mfma_f32_32x32x16_bf16 v[48:63], v[174:177], v[150:153], v[48:63]
	v_mfma_f32_32x32x16_bf16 v[32:47], v[174:177], v[154:157], v[32:47]
	v_mfma_f32_32x32x16_bf16 v[16:31], v[174:177], v[158:161], v[16:31]
	v_mfma_f32_32x32x16_bf16 v[0:15], v[174:177], v[162:165], v[0:15]
	v_add_u32_e32 v162, v166, v230
	v_add_u32_e32 v166, v167, v230
	ds_read_b128 v[150:153], v162
	ds_read_b128 v[154:157], v162 offset:4096
	ds_read_b128 v[158:161], v162 offset:8192
	ds_read_b128 v[162:165], v162 offset:12288
	ds_read_b128 v[170:173], v166 offset:32768
	ds_read_b128 v[174:177], v166 offset:36864
	s_waitcnt lgkmcnt(1)
	v_mfma_f32_32x32x16_bf16 v[112:127], v[170:173], v[150:153], v[112:127]
	v_mfma_f32_32x32x16_bf16 v[96:111], v[170:173], v[154:157], v[96:111]
	v_mfma_f32_32x32x16_bf16 v[80:95], v[170:173], v[158:161], v[80:95]
	v_mfma_f32_32x32x16_bf16 v[64:79], v[170:173], v[162:165], v[64:79]
	s_waitcnt lgkmcnt(0)
	v_mfma_f32_32x32x16_bf16 v[48:63], v[174:177], v[150:153], v[48:63]
	v_mfma_f32_32x32x16_bf16 v[32:47], v[174:177], v[154:157], v[32:47]
	v_mfma_f32_32x32x16_bf16 v[16:31], v[174:177], v[158:161], v[16:31]
	v_mfma_f32_32x32x16_bf16 v[0:15], v[174:177], v[162:165], v[0:15]
	s_mov_b32 s0, s1
	s_cbranch_scc1 .LBB0_717
	s_add_i32 s21, s21, s78
	s_cmpk_gt_i32 s21, 0xff
	s_waitcnt vmcnt(0)
	s_barrier
	s_cselect_b64 s[2:3], -1, 0
	s_and_b64 vcc, exec, s[2:3]
	s_cbranch_vccnz .LBB0_720
	s_lshl_b32 s0, s21, 3
	s_and_b32 s0, s0, 56
	s_ashr_i32 s1, s21, 5
	s_add_i32 s8, s0, s1
	s_ashr_i32 s0, s8, 5
	s_ashr_i32 s1, s0, 31
	s_lshl_b32 s9, s21, 5
	v_lshl_add_u32 v130, s8, 8, v207
	s_and_b32 s9, s9, 0x300
	s_lshl_b64 s[0:1], s[0:1], 21
	v_ashrrev_i32_e32 v131, 31, v130
	v_lshlrev_b64 v[134:135], 11, v[130:131]
	s_cmp_lg_u32 16, -1
	v_lshl_add_u64 v[128:129], v[144:145], 0, s[0:1]
	v_lshl_add_u64 v[134:135], v[146:147], 0, v[134:135]
	v_readfirstlane_b32 s0, v209
	s_cselect_b32 s1, 16, 0
	s_add_i32 s0, s0, s1
	s_mov_b32 s1, m0
	s_mov_b32 m0, s0
	s_nop 0
	global_load_lds_dwordx4 v[134:135], off
	s_mov_b32 m0, s1
	v_add_u32_e32 v134, 64, v130
	v_ashrrev_i32_e32 v135, 31, v134
	v_lshlrev_b64 v[134:135], 11, v[134:135]
	v_lshl_add_u64 v[134:135], v[146:147], 0, v[134:135]
	s_add_i32 s1, s0, 0x2000
	s_mov_b32 s8, m0
	s_mov_b32 m0, s1
	s_nop 0
	global_load_lds_dwordx4 v[134:135], off
	s_mov_b32 m0, s8
	v_add_u32_e32 v134, 0x80, v130
	v_add_u32_e32 v130, 0xc0, v130
	v_ashrrev_i32_e32 v135, 31, v134
	v_ashrrev_i32_e32 v131, 31, v130
	v_add_u32_e32 v132, s9, v208
	v_lshlrev_b64 v[134:135], 11, v[134:135]
	v_lshlrev_b64 v[130:131], 11, v[130:131]
	v_lshl_add_u64 v[134:135], v[146:147], 0, v[134:135]
	s_add_i32 s1, s0, 0x4000
	s_mov_b32 s8, m0
	s_mov_b32 m0, s1
	s_nop 0
	global_load_lds_dwordx4 v[134:135], off
	s_mov_b32 m0, s8
	v_lshl_add_u64 v[130:131], v[146:147], 0, v[130:131]
	v_ashrrev_i32_e32 v133, 31, v132
	s_add_i32 s1, s0, 0x6000
	s_mov_b32 s8, m0
	s_mov_b32 m0, s1
	s_nop 0
	global_load_lds_dwordx4 v[130:131], off
	s_mov_b32 m0, s8
	v_lshlrev_b64 v[130:131], 11, v[132:133]
	v_lshl_add_u64 v[128:129], v[128:129], 0, v[130:131]
	v_lshl_add_u64 v[130:131], v[128:129], 0, s[34:35]
	s_add_i32 s1, s0, 0x8000
	s_mov_b32 s8, m0
	s_mov_b32 m0, s1
	s_nop 0
	global_load_lds_dwordx4 v[130:131], off
	s_mov_b32 m0, s8
	v_lshl_add_u64 v[130:131], v[128:129], 0, s[38:39]
	s_add_i32 s1, s0, 0xa000
	s_mov_b32 s8, m0
	s_mov_b32 m0, s1
	s_nop 0
	global_load_lds_dwordx4 v[130:131], off
	s_mov_b32 m0, s8
	v_lshl_add_u64 v[130:131], v[128:129], 0, s[36:37]
	s_add_i32 s1, s0, 0xc000
	s_mov_b32 s8, m0
	s_mov_b32 m0, s1
	s_nop 0
	global_load_lds_dwordx4 v[130:131], off
	s_mov_b32 m0, s8
	v_lshl_add_u64 v[128:129], v[128:129], 0, s[40:41]
	s_add_i32 s0, s0, 0xe000
	s_mov_b32 s1, m0
	s_mov_b32 m0, s0
	s_nop 0
	global_load_lds_dwordx4 v[128:129], off
	s_mov_b32 m0, s1
	s_mov_b64 s[8:9], -1

.LBB0_745:
	s_add_i32 s1, s0, 0x10000
	s_and_b32 s16, s1, 0x10000
	s_and_b32 s0, s0, 0x10000
	s_add_i32 s0, s0, 16
	v_add_u32_e32 v224, s16, v161
	s_nop 0
	v_readfirstlane_b32 s16, v224
	s_waitcnt vmcnt(0)
	s_barrier
	v_add_u32_e32 v133, s0, v151
	v_add_u32_e32 v168, v133, v171
	ds_read_b128 v[180:183], v168
	ds_read_b128 v[202:205], v168 offset:4096
	ds_read_b128 v[206:209], v168 offset:8192
	ds_read_b128 v[210:213], v168 offset:12288
	v_add_u32_e32 v168, s0, v155
	v_add_u32_e32 v190, v168, v171
	ds_read_b128 v[214:217], v190 offset:32768
	ds_read_b128 v[218:221], v190 offset:36864
	v_lshl_add_u64 v[222:223], v[148:149], 0, s[2:3]
	s_mov_b32 m0, s16
	s_nop 0
	global_load_lds_dwordx4 v[222:223], off
	s_waitcnt lgkmcnt(1)
	v_mfma_f32_32x32x16_bf16 v[112:127], v[214:217], v[180:183], v[112:127]
	v_lshl_add_u64 v[222:223], v[146:147], 0, s[2:3]
	s_add_i32 s17, s16, 0x2000
	s_mov_b32 m0, s17
	s_nop 0
	global_load_lds_dwordx4 v[222:223], off
	v_add_u32_e32 v190, v133, v172
	v_mfma_f32_32x32x16_bf16 v[96:111], v[214:217], v[202:205], v[96:111]
	v_mfma_f32_32x32x16_bf16 v[64:79], v[214:217], v[206:209], v[64:79]
	v_lshl_add_u64 v[222:223], v[144:145], 0, s[2:3]
	s_add_i32 s17, s16, 0x4000
	s_mov_b32 m0, s17
	s_nop 0
	global_load_lds_dwordx4 v[222:223], off
	v_mfma_f32_32x32x16_bf16 v[32:47], v[214:217], v[210:213], v[32:47]
	s_waitcnt lgkmcnt(0)
	v_mfma_f32_32x32x16_bf16 v[80:95], v[218:221], v[180:183], v[80:95]
	v_lshl_add_u64 v[222:223], v[142:143], 0, s[2:3]
	s_add_i32 s17, s16, 0x6000
	s_mov_b32 m0, s17
	s_nop 0
	global_load_lds_dwordx4 v[222:223], off
	v_mfma_f32_32x32x16_bf16 v[48:63], v[218:221], v[202:205], v[48:63]
	v_mfma_f32_32x32x16_bf16 v[16:31], v[218:221], v[206:209], v[16:31]
	v_lshl_add_u64 v[222:223], v[140:141], 0, s[2:3]
	s_add_i32 s17, s16, 0x8000
	s_mov_b32 m0, s17
	s_nop 0
	global_load_lds_dwordx4 v[222:223], off
	v_mfma_f32_32x32x16_bf16 v[0:15], v[218:221], v[210:213], v[0:15]
	ds_read_b128 v[180:183], v190
	ds_read_b128 v[202:205], v190 offset:4096
	ds_read_b128 v[206:209], v190 offset:8192
	ds_read_b128 v[210:213], v190 offset:12288
	v_add_u32_e32 v190, v168, v172
	ds_read_b128 v[214:217], v190 offset:32768
	ds_read_b128 v[218:221], v190 offset:36864
	v_add_u32_e32 v190, v133, v173
	v_add_u32_e32 v133, v133, v174
	s_waitcnt lgkmcnt(1)
	v_mfma_f32_32x32x16_bf16 v[112:127], v[214:217], v[180:183], v[112:127]
	v_lshl_add_u64 v[222:223], v[138:139], 0, s[2:3]
	s_add_i32 s17, s16, 0xa000
	s_mov_b32 m0, s17
	s_nop 0
	global_load_lds_dwordx4 v[222:223], off
	v_mfma_f32_32x32x16_bf16 v[96:111], v[214:217], v[202:205], v[96:111]
	v_mfma_f32_32x32x16_bf16 v[64:79], v[214:217], v[206:209], v[64:79]
	v_lshl_add_u64 v[222:223], v[136:137], 0, s[2:3]
	s_add_i32 s17, s16, 0xc000
	s_mov_b32 m0, s17
	s_nop 0
	global_load_lds_dwordx4 v[222:223], off
	v_mfma_f32_32x32x16_bf16 v[32:47], v[214:217], v[210:213], v[32:47]
	s_waitcnt lgkmcnt(0)
	v_mfma_f32_32x32x16_bf16 v[80:95], v[218:221], v[180:183], v[80:95]
	v_lshl_add_u64 v[222:223], v[134:135], 0, s[2:3]
	s_add_i32 s17, s16, 0xe000
	s_mov_b32 m0, s17
	s_nop 0
	global_load_lds_dwordx4 v[222:223], off
	s_add_u32 s2, s2, 0x80
	s_addc_u32 s3, s3, 0
	s_cmpk_eq_i32 s2, 0x780
	v_mfma_f32_32x32x16_bf16 v[48:63], v[218:221], v[202:205], v[48:63]
	v_mfma_f32_32x32x16_bf16 v[16:31], v[218:221], v[206:209], v[16:31]
	v_mfma_f32_32x32x16_bf16 v[0:15], v[218:221], v[210:213], v[0:15]
	ds_read_b128 v[180:183], v190
	ds_read_b128 v[202:205], v190 offset:4096
	ds_read_b128 v[206:209], v190 offset:8192
	ds_read_b128 v[210:213], v190 offset:12288
	v_add_u32_e32 v190, v168, v173
	ds_read_b128 v[214:217], v190 offset:32768
	ds_read_b128 v[218:221], v190 offset:36864
	s_waitcnt lgkmcnt(1)
	v_mfma_f32_32x32x16_bf16 v[112:127], v[214:217], v[180:183], v[112:127]
	v_mfma_f32_32x32x16_bf16 v[96:111], v[214:217], v[202:205], v[96:111]
	v_mfma_f32_32x32x16_bf16 v[64:79], v[214:217], v[206:209], v[64:79]
	v_mfma_f32_32x32x16_bf16 v[32:47], v[214:217], v[210:213], v[32:47]
	s_waitcnt lgkmcnt(0)
	v_mfma_f32_32x32x16_bf16 v[80:95], v[218:221], v[180:183], v[80:95]
	v_mfma_f32_32x32x16_bf16 v[48:63], v[218:221], v[202:205], v[48:63]
	v_mfma_f32_32x32x16_bf16 v[16:31], v[218:221], v[206:209], v[16:31]
	v_mfma_f32_32x32x16_bf16 v[0:15], v[218:221], v[210:213], v[0:15]
	ds_read_b128 v[180:183], v133
	ds_read_b128 v[202:205], v133 offset:4096
	ds_read_b128 v[206:209], v133 offset:8192
	ds_read_b128 v[210:213], v133 offset:12288
	v_add_u32_e32 v133, v168, v174
	ds_read_b128 v[214:217], v133 offset:32768
	ds_read_b128 v[218:221], v133 offset:36864
	s_waitcnt lgkmcnt(1)
	v_mfma_f32_32x32x16_bf16 v[112:127], v[214:217], v[180:183], v[112:127]
	v_mfma_f32_32x32x16_bf16 v[96:111], v[214:217], v[202:205], v[96:111]
	v_mfma_f32_32x32x16_bf16 v[64:79], v[214:217], v[206:209], v[64:79]
	v_mfma_f32_32x32x16_bf16 v[32:47], v[214:217], v[210:213], v[32:47]
	s_waitcnt lgkmcnt(0)
	v_mfma_f32_32x32x16_bf16 v[80:95], v[218:221], v[180:183], v[80:95]
	v_mfma_f32_32x32x16_bf16 v[48:63], v[218:221], v[202:205], v[48:63]
	v_mfma_f32_32x32x16_bf16 v[16:31], v[218:221], v[206:209], v[16:31]
	v_mfma_f32_32x32x16_bf16 v[0:15], v[218:221], v[210:213], v[0:15]
	s_mov_b32 s0, s1
	s_cbranch_scc0 .LBB0_745
	s_waitcnt vmcnt(0)
	s_barrier
	v_mov_b32_e32 v133, 0x358637bd
	s_and_saveexec_b64 s[2:3], s[6:7]
	s_cbranch_execz .LBB0_748
	v_add_u32_e32 v134, s19, v150
	v_ashrrev_i32_e32 v135, 31, v134
	v_lshlrev_b64 v[134:135], 6, v[134:135]
	v_lshl_add_u64 v[146:147], s[12:13], 0, v[134:135]
	global_load_dwordx4 v[134:137], v[146:147], off
	global_load_dwordx4 v[138:141], v[146:147], off offset:16
	global_load_dwordx4 v[142:145], v[146:147], off offset:32
	s_nop 0
	global_load_dwordx4 v[146:149], v[146:147], off offset:48
	s_waitcnt vmcnt(3)
	v_mov_b32_e32 v180, v135
	v_mov_b32_e32 v181, v136
	v_mov_b32_e32 v135, v137
	v_pk_add_f32 v[134:135], v[180:181], v[134:135]
	s_waitcnt vmcnt(2)
	v_mov_b32_e32 v182, v139
	v_mov_b32_e32 v183, v140
	v_mov_b32_e32 v139, v141
	v_add_f32_e32 v133, 0, v134
	v_pk_add_f32 v[136:137], v[182:183], v[138:139]
	v_add_f32_e32 v133, v133, v135
	s_waitcnt vmcnt(1)
	v_mov_b32_e32 v202, v143
	v_mov_b32_e32 v203, v144
	v_mov_b32_e32 v143, v145
	v_add_f32_e32 v133, v133, v136
	v_pk_add_f32 v[138:139], v[202:203], v[142:143]
	v_add_f32_e32 v133, v133, v137
	s_waitcnt vmcnt(0)
	v_mov_b32_e32 v204, v147
	v_mov_b32_e32 v205, v148
	v_mov_b32_e32 v147, v149
	v_add_f32_e32 v133, v133, v138
	v_add_f32_e32 v133, v133, v139
	v_pk_add_f32 v[134:135], v[204:205], v[146:147]
	s_nop 0
	v_add_f32_e32 v133, v133, v134
	v_add_f32_e32 v133, v133, v135
	v_fmamk_f32 v133, v133, 0x3a800000, v187

.LBB0_778:
	s_add_i32 s1, s0, 0x10000
	s_and_b32 s11, s1, 0x10000
	s_and_b32 s0, s0, 0x10000
	s_add_i32 s0, s0, 16
	v_add_u32_e32 v190, s11, v210
	s_nop 0
	v_readfirstlane_b32 s11, v190
	s_waitcnt vmcnt(0)
	s_barrier
	v_add_u32_e32 v166, s0, v182
	v_add_u32_e32 v167, s0, v204
	v_add_u32_e32 v162, v166, v227
	v_add_u32_e32 v168, v167, v227
	ds_read_b128 v[150:153], v162
	ds_read_b128 v[154:157], v162 offset:4096
	ds_read_b128 v[158:161], v162 offset:8192
	ds_read_b128 v[162:165], v162 offset:12288
	ds_read_b128 v[170:173], v168 offset:32768
	ds_read_b128 v[174:177], v168 offset:36864
	v_lshl_add_u64 v[178:179], v[142:143], 0, s[2:3]
	s_mov_b32 m0, s11
	s_nop 0
	global_load_lds_dwordx4 v[178:179], off
	s_waitcnt lgkmcnt(1)
	v_mfma_f32_32x32x16_bf16 v[112:127], v[170:173], v[150:153], v[112:127]
	v_lshl_add_u64 v[178:179], v[140:141], 0, s[2:3]
	s_add_i32 s12, s11, 0x2000
	s_mov_b32 m0, s12
	s_nop 0
	global_load_lds_dwordx4 v[178:179], off
	v_add_u32_e32 v168, v167, v228
	v_mfma_f32_32x32x16_bf16 v[96:111], v[170:173], v[154:157], v[96:111]
	v_mfma_f32_32x32x16_bf16 v[80:95], v[170:173], v[158:161], v[80:95]
	v_lshl_add_u64 v[178:179], v[138:139], 0, s[2:3]
	s_add_i32 s12, s11, 0x4000
	s_mov_b32 m0, s12
	s_nop 0
	global_load_lds_dwordx4 v[178:179], off
	v_mfma_f32_32x32x16_bf16 v[64:79], v[170:173], v[162:165], v[64:79]
	s_waitcnt lgkmcnt(0)
	v_mfma_f32_32x32x16_bf16 v[48:63], v[174:177], v[150:153], v[48:63]
	v_lshl_add_u64 v[178:179], v[136:137], 0, s[2:3]
	s_add_i32 s12, s11, 0x6000
	s_mov_b32 m0, s12
	s_nop 0
	global_load_lds_dwordx4 v[178:179], off
	v_mfma_f32_32x32x16_bf16 v[32:47], v[174:177], v[154:157], v[32:47]
	v_mfma_f32_32x32x16_bf16 v[16:31], v[174:177], v[158:161], v[16:31]
	v_lshl_add_u64 v[178:179], v[134:135], 0, s[2:3]
	s_add_i32 s12, s11, 0x8000
	s_mov_b32 m0, s12
	s_nop 0
	global_load_lds_dwordx4 v[178:179], off
	v_mfma_f32_32x32x16_bf16 v[0:15], v[174:177], v[162:165], v[0:15]
	v_add_u32_e32 v162, v166, v228
	ds_read_b128 v[150:153], v162
	ds_read_b128 v[154:157], v162 offset:4096
	ds_read_b128 v[158:161], v162 offset:8192
	ds_read_b128 v[162:165], v162 offset:12288
	ds_read_b128 v[170:173], v168 offset:32768
	ds_read_b128 v[174:177], v168 offset:36864
	v_add_u32_e32 v168, v167, v229
	s_waitcnt lgkmcnt(1)
	v_mfma_f32_32x32x16_bf16 v[112:127], v[170:173], v[150:153], v[112:127]
	v_lshl_add_u64 v[178:179], v[132:133], 0, s[2:3]
	s_add_i32 s12, s11, 0xa000
	s_mov_b32 m0, s12
	s_nop 0
	global_load_lds_dwordx4 v[178:179], off
	v_mfma_f32_32x32x16_bf16 v[96:111], v[170:173], v[154:157], v[96:111]
	v_mfma_f32_32x32x16_bf16 v[80:95], v[170:173], v[158:161], v[80:95]
	v_lshl_add_u64 v[178:179], v[130:131], 0, s[2:3]
	s_add_i32 s12, s11, 0xc000
	s_mov_b32 m0, s12
	s_nop 0
	global_load_lds_dwordx4 v[178:179], off
	v_mfma_f32_32x32x16_bf16 v[64:79], v[170:173], v[162:165], v[64:79]
	s_waitcnt lgkmcnt(0)
	v_mfma_f32_32x32x16_bf16 v[48:63], v[174:177], v[150:153], v[48:63]
	v_lshl_add_u64 v[178:179], v[128:129], 0, s[2:3]
	s_add_i32 s12, s11, 0xe000
	s_mov_b32 m0, s12
	s_nop 0
	global_load_lds_dwordx4 v[178:179], off
	s_add_u32 s2, s2, 0x80
	s_addc_u32 s3, s3, 0
	s_cmpk_lg_i32 s2, 0x780
	v_mfma_f32_32x32x16_bf16 v[32:47], v[174:177], v[154:157], v[32:47]
	v_mfma_f32_32x32x16_bf16 v[16:31], v[174:177], v[158:161], v[16:31]
	v_mfma_f32_32x32x16_bf16 v[0:15], v[174:177], v[162:165], v[0:15]
	v_add_u32_e32 v162, v166, v229
	ds_read_b128 v[150:153], v162
	ds_read_b128 v[154:157], v162 offset:4096
	ds_read_b128 v[158:161], v162 offset:8192
	ds_read_b128 v[162:165], v162 offset:12288
	ds_read_b128 v[170:173], v168 offset:32768
	ds_read_b128 v[174:177], v168 offset:36864
	s_waitcnt lgkmcnt(1)
	v_mfma_f32_32x32x16_bf16 v[112:127], v[170:173], v[150:153], v[112:127]
	v_mfma_f32_32x32x16_bf16 v[96:111], v[170:173], v[154:157], v[96:111]
	v_mfma_f32_32x32x16_bf16 v[80:95], v[170:173], v[158:161], v[80:95]
	v_mfma_f32_32x32x16_bf16 v[64:79], v[170:173], v[162:165], v[64:79]
	s_waitcnt lgkmcnt(0)
	v_mfma_f32_32x32x16_bf16 v[48:63], v[174:177], v[150:153], v[48:63]
	v_mfma_f32_32x32x16_bf16 v[32:47], v[174:177], v[154:157], v[32:47]
	v_mfma_f32_32x32x16_bf16 v[16:31], v[174:177], v[158:161], v[16:31]
	v_mfma_f32_32x32x16_bf16 v[0:15], v[174:177], v[162:165], v[0:15]
	v_add_u32_e32 v162, v166, v230
	v_add_u32_e32 v166, v167, v230
	ds_read_b128 v[150:153], v162
	ds_read_b128 v[154:157], v162 offset:4096
	ds_read_b128 v[158:161], v162 offset:8192
	ds_read_b128 v[162:165], v162 offset:12288
	ds_read_b128 v[170:173], v166 offset:32768
	ds_read_b128 v[174:177], v166 offset:36864
	s_waitcnt lgkmcnt(1)
	v_mfma_f32_32x32x16_bf16 v[112:127], v[170:173], v[150:153], v[112:127]
	v_mfma_f32_32x32x16_bf16 v[96:111], v[170:173], v[154:157], v[96:111]
	v_mfma_f32_32x32x16_bf16 v[80:95], v[170:173], v[158:161], v[80:95]
	v_mfma_f32_32x32x16_bf16 v[64:79], v[170:173], v[162:165], v[64:79]
	s_waitcnt lgkmcnt(0)
	v_mfma_f32_32x32x16_bf16 v[48:63], v[174:177], v[150:153], v[48:63]
	v_mfma_f32_32x32x16_bf16 v[32:47], v[174:177], v[154:157], v[32:47]
	v_mfma_f32_32x32x16_bf16 v[16:31], v[174:177], v[158:161], v[16:31]
	v_mfma_f32_32x32x16_bf16 v[0:15], v[174:177], v[162:165], v[0:15]
	s_mov_b32 s0, s1
	s_cbranch_scc1 .LBB0_778
	s_add_i32 s21, s21, s78
	s_cmpk_gt_i32 s21, 0xff
	s_waitcnt vmcnt(0)
	s_barrier
	s_cselect_b64 s[2:3], -1, 0
	s_and_b64 vcc, exec, s[2:3]
	s_cbranch_vccnz .LBB0_781
	s_lshl_b32 s0, s21, 3
	s_lshr_b32 s1, s21, 5
	s_and_b32 s0, s0, 56
	s_add_i32 s0, s0, s1
	s_lshl_b32 s8, s21, 5
	v_lshl_add_u32 v130, s0, 8, v207
	s_and_b32 s8, s8, 0x300
	v_ashrrev_i32_e32 v131, 31, v130
	v_lshlrev_b64 v[132:133], 11, v[130:131]
	s_cmp_lg_u32 16, -1
	v_lshl_add_u64 v[132:133], v[146:147], 0, v[132:133]
	v_readfirstlane_b32 s0, v209
	s_cselect_b32 s1, 16, 0
	s_add_i32 s0, s0, s1
	s_mov_b32 s1, m0
	s_mov_b32 m0, s0
	s_nop 0
	global_load_lds_dwordx4 v[132:133], off
	s_mov_b32 m0, s1
	v_add_u32_e32 v132, 64, v130
	v_ashrrev_i32_e32 v133, 31, v132
	v_lshlrev_b64 v[132:133], 11, v[132:133]
	v_lshl_add_u64 v[132:133], v[146:147], 0, v[132:133]
	v_add_u32_e32 v128, s8, v208
	s_add_i32 s1, s0, 0x2000
	s_mov_b32 s8, m0
	s_mov_b32 m0, s1
	s_nop 0
	global_load_lds_dwordx4 v[132:133], off
	s_mov_b32 m0, s8
	v_add_u32_e32 v132, 0x80, v130
	v_ashrrev_i32_e32 v133, 31, v132
	v_add_u32_e32 v130, 0xc0, v130
	v_lshlrev_b64 v[132:133], 11, v[132:133]
	v_ashrrev_i32_e32 v131, 31, v130
	v_ashrrev_i32_e32 v129, 31, v128
	v_lshl_add_u64 v[132:133], v[146:147], 0, v[132:133]
	s_add_i32 s1, s0, 0x4000
	s_mov_b32 s8, m0
	s_mov_b32 m0, s1
	s_nop 0
	global_load_lds_dwordx4 v[132:133], off
	s_mov_b32 m0, s8
	v_lshlrev_b64 v[130:131], 11, v[130:131]
	v_lshlrev_b64 v[128:129], 11, v[128:129]
	v_lshl_add_u64 v[130:131], v[146:147], 0, v[130:131]
	s_add_i32 s1, s0, 0x6000
	s_mov_b32 s8, m0
	s_mov_b32 m0, s1
	s_nop 0
	global_load_lds_dwordx4 v[130:131], off
	s_mov_b32 m0, s8
	v_lshl_add_u64 v[128:129], v[144:145], 0, v[128:129]
	v_lshl_add_u64 v[130:131], v[128:129], 0, s[34:35]
	s_add_i32 s1, s0, 0x8000
	s_mov_b32 s8, m0
	s_mov_b32 m0, s1
	s_nop 0
	global_load_lds_dwordx4 v[130:131], off
	s_mov_b32 m0, s8
	v_lshl_add_u64 v[130:131], v[128:129], 0, s[38:39]
	s_add_i32 s1, s0, 0xa000
	s_mov_b32 s8, m0
	s_mov_b32 m0, s1
	s_nop 0
	global_load_lds_dwordx4 v[130:131], off
	s_mov_b32 m0, s8
	v_lshl_add_u64 v[130:131], v[128:129], 0, s[36:37]
	s_add_i32 s1, s0, 0xc000
	s_mov_b32 s8, m0
	s_mov_b32 m0, s1
	s_nop 0
	global_load_lds_dwordx4 v[130:131], off
	s_mov_b32 m0, s8
	v_lshl_add_u64 v[128:129], v[128:129], 0, s[40:41]
	s_add_i32 s0, s0, 0xe000
	s_mov_b32 s1, m0
	s_mov_b32 m0, s0
	s_nop 0
	global_load_lds_dwordx4 v[128:129], off
	s_mov_b32 m0, s1
	s_mov_b64 s[8:9], -1

.LBB0_1265:
	s_add_i32 s1, s0, 0x10000
	s_and_b32 s12, s1, 0x10000
	s_and_b32 s0, s0, 0x10000
	s_add_i32 s0, s0, 16
	v_add_u32_e32 v190, s12, v160
	s_nop 0
	v_readfirstlane_b32 s12, v190
	s_waitcnt vmcnt(0)
	s_barrier
	v_add_u32_e32 v177, s0, v150
	v_add_u32_e32 v182, v177, v166
	ds_read_b128 v[178:181], v182
	ds_read_b128 v[202:205], v182 offset:4096
	ds_read_b128 v[206:209], v182 offset:8192
	ds_read_b128 v[210:213], v182 offset:12288
	v_add_u32_e32 v182, s0, v154
	v_add_u32_e32 v183, v182, v166
	ds_read_b128 v[214:217], v183 offset:32768
	ds_read_b128 v[218:221], v183 offset:36864
	v_lshl_add_u64 v[222:223], v[148:149], 0, s[2:3]
	s_mov_b32 m0, s12
	s_nop 0
	global_load_lds_dwordx4 v[222:223], off
	s_waitcnt lgkmcnt(1)
	v_mfma_f32_32x32x16_bf16 v[112:127], v[214:217], v[178:181], v[112:127]
	v_lshl_add_u64 v[222:223], v[146:147], 0, s[2:3]
	s_add_i32 s13, s12, 0x2000
	s_mov_b32 m0, s13
	s_nop 0
	global_load_lds_dwordx4 v[222:223], off
	v_add_u32_e32 v183, v177, v167
	v_mfma_f32_32x32x16_bf16 v[80:95], v[214:217], v[202:205], v[80:95]
	v_mfma_f32_32x32x16_bf16 v[48:63], v[214:217], v[206:209], v[48:63]
	v_lshl_add_u64 v[222:223], v[144:145], 0, s[2:3]
	s_add_i32 s13, s12, 0x4000
	s_mov_b32 m0, s13
	s_nop 0
	global_load_lds_dwordx4 v[222:223], off
	v_mfma_f32_32x32x16_bf16 v[16:31], v[214:217], v[210:213], v[16:31]
	s_waitcnt lgkmcnt(0)
	v_mfma_f32_32x32x16_bf16 v[96:111], v[218:221], v[178:181], v[96:111]
	v_lshl_add_u64 v[222:223], v[142:143], 0, s[2:3]
	s_add_i32 s13, s12, 0x6000
	s_mov_b32 m0, s13
	s_nop 0
	global_load_lds_dwordx4 v[222:223], off
	v_mfma_f32_32x32x16_bf16 v[64:79], v[218:221], v[202:205], v[64:79]
	v_mfma_f32_32x32x16_bf16 v[32:47], v[218:221], v[206:209], v[32:47]
	v_lshl_add_u64 v[222:223], v[140:141], 0, s[2:3]
	s_add_i32 s13, s12, 0x8000
	s_mov_b32 m0, s13
	s_nop 0
	global_load_lds_dwordx4 v[222:223], off
	v_mfma_f32_32x32x16_bf16 v[0:15], v[218:221], v[210:213], v[0:15]
	ds_read_b128 v[178:181], v183
	ds_read_b128 v[202:205], v183 offset:4096
	ds_read_b128 v[206:209], v183 offset:8192
	ds_read_b128 v[210:213], v183 offset:12288
	v_add_u32_e32 v183, v182, v167
	ds_read_b128 v[214:217], v183 offset:32768
	ds_read_b128 v[218:221], v183 offset:36864
	v_add_u32_e32 v183, v177, v170
	v_add_u32_e32 v177, v177, v171
	s_waitcnt lgkmcnt(1)
	v_mfma_f32_32x32x16_bf16 v[112:127], v[214:217], v[178:181], v[112:127]
	v_lshl_add_u64 v[222:223], v[138:139], 0, s[2:3]
	s_add_i32 s13, s12, 0xa000
	s_mov_b32 m0, s13
	s_nop 0
	global_load_lds_dwordx4 v[222:223], off
	v_mfma_f32_32x32x16_bf16 v[80:95], v[214:217], v[202:205], v[80:95]
	v_mfma_f32_32x32x16_bf16 v[48:63], v[214:217], v[206:209], v[48:63]
	v_lshl_add_u64 v[222:223], v[136:137], 0, s[2:3]
	s_add_i32 s13, s12, 0xc000
	s_mov_b32 m0, s13
	s_nop 0
	global_load_lds_dwordx4 v[222:223], off
	v_mfma_f32_32x32x16_bf16 v[16:31], v[214:217], v[210:213], v[16:31]
	s_waitcnt lgkmcnt(0)
	v_mfma_f32_32x32x16_bf16 v[96:111], v[218:221], v[178:181], v[96:111]
	v_lshl_add_u64 v[222:223], v[134:135], 0, s[2:3]
	s_add_i32 s13, s12, 0xe000
	s_mov_b32 m0, s13
	s_nop 0
	global_load_lds_dwordx4 v[222:223], off
	s_add_u32 s2, s2, 0x80
	s_addc_u32 s3, s3, 0
	s_cmpk_eq_i32 s2, 0x780
	v_mfma_f32_32x32x16_bf16 v[64:79], v[218:221], v[202:205], v[64:79]
	v_mfma_f32_32x32x16_bf16 v[32:47], v[218:221], v[206:209], v[32:47]
	v_mfma_f32_32x32x16_bf16 v[0:15], v[218:221], v[210:213], v[0:15]
	ds_read_b128 v[178:181], v183
	ds_read_b128 v[202:205], v183 offset:4096
	ds_read_b128 v[206:209], v183 offset:8192
	ds_read_b128 v[210:213], v183 offset:12288
	v_add_u32_e32 v183, v182, v170
	ds_read_b128 v[214:217], v183 offset:32768
	ds_read_b128 v[218:221], v183 offset:36864
	s_waitcnt lgkmcnt(1)
	v_mfma_f32_32x32x16_bf16 v[112:127], v[214:217], v[178:181], v[112:127]
	v_mfma_f32_32x32x16_bf16 v[80:95], v[214:217], v[202:205], v[80:95]
	v_mfma_f32_32x32x16_bf16 v[48:63], v[214:217], v[206:209], v[48:63]
	v_mfma_f32_32x32x16_bf16 v[16:31], v[214:217], v[210:213], v[16:31]
	s_waitcnt lgkmcnt(0)
	v_mfma_f32_32x32x16_bf16 v[96:111], v[218:221], v[178:181], v[96:111]
	v_mfma_f32_32x32x16_bf16 v[64:79], v[218:221], v[202:205], v[64:79]
	v_mfma_f32_32x32x16_bf16 v[32:47], v[218:221], v[206:209], v[32:47]
	v_mfma_f32_32x32x16_bf16 v[0:15], v[218:221], v[210:213], v[0:15]
	ds_read_b128 v[178:181], v177
	ds_read_b128 v[202:205], v177 offset:4096
	ds_read_b128 v[206:209], v177 offset:8192
	ds_read_b128 v[210:213], v177 offset:12288
	v_add_u32_e32 v177, v182, v171
	ds_read_b128 v[214:217], v177 offset:32768
	ds_read_b128 v[218:221], v177 offset:36864
	s_waitcnt lgkmcnt(1)
	v_mfma_f32_32x32x16_bf16 v[112:127], v[214:217], v[178:181], v[112:127]
	v_mfma_f32_32x32x16_bf16 v[80:95], v[214:217], v[202:205], v[80:95]
	v_mfma_f32_32x32x16_bf16 v[48:63], v[214:217], v[206:209], v[48:63]
	v_mfma_f32_32x32x16_bf16 v[16:31], v[214:217], v[210:213], v[16:31]
	s_waitcnt lgkmcnt(0)
	v_mfma_f32_32x32x16_bf16 v[96:111], v[218:221], v[178:181], v[96:111]
	v_mfma_f32_32x32x16_bf16 v[64:79], v[218:221], v[202:205], v[64:79]
	v_mfma_f32_32x32x16_bf16 v[32:47], v[218:221], v[206:209], v[32:47]
	v_mfma_f32_32x32x16_bf16 v[0:15], v[218:221], v[210:213], v[0:15]
	s_mov_b32 s0, s1
	s_cbranch_scc0 .LBB0_1265
	s_waitcnt vmcnt(0)
	s_barrier
	v_mov_b32_e32 v134, 0x358637bd
	s_and_saveexec_b64 s[2:3], s[6:7]
	s_cbranch_execz .LBB0_1268
	v_add_u32_e32 v134, s10, v129
	v_ashrrev_i32_e32 v135, 31, v134
	v_lshlrev_b64 v[134:135], 6, v[134:135]
	v_lshl_add_u64 v[146:147], s[72:73], 0, v[134:135]
	global_load_dwordx4 v[134:137], v[146:147], off
	global_load_dwordx4 v[138:141], v[146:147], off offset:16
	global_load_dwordx4 v[142:145], v[146:147], off offset:32
	s_nop 0
	global_load_dwordx4 v[146:149], v[146:147], off offset:48
	s_waitcnt vmcnt(3)
	v_mov_b32_e32 v178, v135
	v_mov_b32_e32 v179, v136
	v_mov_b32_e32 v135, v137
	v_pk_add_f32 v[134:135], v[178:179], v[134:135]
	s_waitcnt vmcnt(2)
	v_mov_b32_e32 v180, v139
	v_mov_b32_e32 v181, v140
	v_mov_b32_e32 v139, v141
	v_add_f32_e32 v134, 0, v134
	v_pk_add_f32 v[136:137], v[180:181], v[138:139]
	v_add_f32_e32 v134, v134, v135
	s_waitcnt vmcnt(1)
	v_mov_b32_e32 v182, v143
	v_mov_b32_e32 v183, v144
	v_mov_b32_e32 v143, v145
	v_add_f32_e32 v134, v134, v136
	v_pk_add_f32 v[138:139], v[182:183], v[142:143]
	v_add_f32_e32 v134, v134, v137
	s_waitcnt vmcnt(0)
	v_mov_b32_e32 v202, v147
	v_mov_b32_e32 v203, v148
	v_mov_b32_e32 v147, v149
	v_add_f32_e32 v134, v134, v138
	v_add_f32_e32 v136, v134, v139
	v_pk_add_f32 v[134:135], v[202:203], v[146:147]
	s_nop 0
	v_add_f32_e32 v134, v136, v134
	v_add_f32_e32 v134, v134, v135
	v_fmamk_f32 v134, v134, 0x3a800000, v187
